# rownorm row loops: all 16 loads of a row issued together with counted vmcnt (was 4 dependent round trips)
# speedup vs baseline: 1.0248x; 1.0091x over previous
; DI float bflo(unsigned u) { return __uint_as_float(u << 16); }
; DI float bfhi(unsigned u) { return __uint_as_float(u & 0xffff0000u); }
; DI float wave_sum(float v) { v += __shfl_xor(v, 32); v += __shfl_xor(v, 16); v += __shfl_xor(v, 8); v += __shfl_xor(v, 4); v += __shfl_xor(v, 2); v += __shfl_xor(v, 1); return v; }
; DI void rownorm_phase(const Params& P, const float* xin, const bf16_t* yin, float* xout, bf16_t* hout, int lg, int gate_idx, const float* w_post,
;                       int lh, int scale_idx, int shift_idx, const float* w_pre, char* smem) {
;     ...
;   for (int row = blockIdx.x * 8 + w; row < S_; row += gridDim.x * 8) {
;     f32x4 xv[8];
; #pragma unroll
;     for (int j = 0; j < 8; ++j) xv[j] = __builtin_nontemporal_load((const f32x4*)(xin + (size_t)row * 2048 + (j * 64 + lane) * 4));
;     if (yin) {
;       f32x4 yv[8]; float ss = 0.f;
; #pragma unroll
;       for (int j = 0; j < 8; ++j) { const u32x2 yb = __builtin_nontemporal_load((const u32x2*)(yin + (size_t)row * 2048 + (j * 64 + lane) * 4)); yv[j] = (f32x4){bflo(yb.x), bfhi(yb.x), bflo(yb.y), bfhi(yb.y)};
;         ss += yv[j].x * yv[j].x + yv[j].y * yv[j].y + yv[j].z * yv[j].z + yv[j].w * yv[j].w; }
;       ss = wave_sum(ss); const float r = rsqrtf(ss * (1.f / 2048.f) + EPS);
.LBB0_887:
	s_or_b64 exec, exec, s[0:1]
	v_ashrrev_i32_e32 v0, 6, v2
	v_readlane_b32 s0, v254, 3
	s_waitcnt lgkmcnt(0)
	s_barrier
	v_add_u32_e32 v36, s0, v0
	s_movk_i32 s0, 0x4000
	v_cmp_gt_i32_e32 vcc, s0, v36
	s_and_saveexec_b64 s[0:1], vcc
	s_movk_i32 s96, 0x5ff
	s_movk_i32 s10, 0x3fff
	s_cbranch_execz .LBB0_890
	v_and_b32_e32 v5, 64, v239
	v_xor_b32_e32 v3, 32, v239
	v_add_u32_e32 v5, 64, v5
	v_cmp_lt_i32_e32 vcc, v3, v5
	v_and_b32_e32 v0, 63, v2
	v_lshlrev_b32_e32 v2, 2, v0
	v_cndmask_b32_e32 v3, v239, v3, vcc
	v_lshlrev_b32_e32 v96, 2, v3
	v_xor_b32_e32 v3, 16, v239
	v_cmp_lt_i32_e32 vcc, v3, v5
	v_readlane_b32 s8, v254, 61
	v_lshlrev_b32_e32 v95, 4, v0
	v_cndmask_b32_e32 v3, v239, v3, vcc
	v_lshlrev_b32_e32 v97, 2, v3
	v_xor_b32_e32 v3, 8, v239
	v_cmp_lt_i32_e32 vcc, v3, v5
	v_or_b32_e32 v4, 0x400, v2
	v_or_b32_e32 v6, 0x500, v2
	v_cndmask_b32_e32 v3, v239, v3, vcc
	v_lshlrev_b32_e32 v98, 2, v3
	v_xor_b32_e32 v3, 4, v239
	v_cmp_lt_i32_e32 vcc, v3, v5
	v_or_b32_e32 v8, 0x600, v2
	v_or_b32_e32 v10, 0x700, v2
	v_cndmask_b32_e32 v3, v239, v3, vcc
	v_lshlrev_b32_e32 v99, 2, v3
	v_xor_b32_e32 v3, 2, v239
	v_cmp_lt_i32_e32 vcc, v3, v5
	v_lshlrev_b32_e32 v0, 3, v0
	v_readlane_b32 s9, v254, 62
	v_cndmask_b32_e32 v3, v239, v3, vcc
	v_lshlrev_b32_e32 v100, 2, v3
	v_xor_b32_e32 v3, 1, v239
	v_cmp_lt_i32_e32 vcc, v3, v5
	v_lshl_add_u64 v[38:39], s[8:9], 0, v[0:1]
	v_lshl_add_u64 v[40:41], s[60:61], 0, v[0:1]
	v_cndmask_b32_e32 v3, v239, v3, vcc
	v_lshlrev_b32_e32 v101, 2, v3
	s_mov_b64 s[8:9], 0
	v_lshlrev_b32_e32 v0, 2, v2
	v_lshlrev_b32_e32 v42, 2, v4
	v_lshlrev_b32_e32 v44, 2, v6
	v_lshlrev_b32_e32 v46, 2, v8
	v_lshlrev_b32_e32 v48, 2, v10
	s_waitcnt vmcnt(0)
.LBB0_889:
	v_ashrrev_i32_e32 v37, 31, v36
	v_lshlrev_b64 v[2:3], 13, v[36:37]
	v_lshl_add_u64 v[2:3], v[34:35], 0, v[2:3]
	v_lshlrev_b64 v[50:51], 12, v[36:37]
	v_lshl_add_u64 v[52:53], v[2:3], 0, v[0:1]
	v_lshl_add_u64 v[86:87], v[38:39], 0, v[50:51]
	global_load_dwordx4 v[30:33], v[52:53], off nt
	global_load_dwordx4 v[26:29], v[52:53], off offset:1024 nt
	global_load_dwordx4 v[22:25], v[52:53], off offset:2048 nt
	global_load_dwordx4 v[18:21], v[52:53], off offset:3072 nt
	global_load_dwordx2 v[62:63], v[86:87], off nt
	v_mov_b32_e32 v43, v1
	v_mov_b32_e32 v45, v1
	v_mov_b32_e32 v47, v1
	v_mov_b32_e32 v49, v1
	v_lshl_add_u64 v[54:55], v[2:3], 0, v[42:43]
	v_lshl_add_u64 v[56:57], v[2:3], 0, v[44:45]
	v_lshl_add_u64 v[58:59], v[2:3], 0, v[46:47]
	v_lshl_add_u64 v[60:61], v[2:3], 0, v[48:49]
	global_load_dwordx4 v[14:17], v[54:55], off nt
	global_load_dwordx4 v[10:13], v[56:57], off nt
	global_load_dwordx4 v[6:9], v[58:59], off nt
	global_load_dwordx4 v[2:5], v[60:61], off nt
	global_load_dwordx2 v[106:107], v[86:87], off offset:512 nt
	global_load_dwordx2 v[108:109], v[86:87], off offset:1024 nt
	global_load_dwordx2 v[110:111], v[86:87], off offset:1536 nt
	global_load_dwordx2 v[88:89], v[86:87], off offset:2048 nt
	global_load_dwordx2 v[66:67], v[86:87], off offset:2560 nt
	global_load_dwordx2 v[102:103], v[86:87], off offset:3072 nt
	global_load_dwordx2 v[92:93], v[86:87], off offset:3584 nt
	s_waitcnt vmcnt(11)
	v_add_u32_e32 v36, s79, v36
	v_lshlrev_b32_e32 v70, 16, v62
	v_and_b32_e32 v71, 0xffff0000, v62
	v_lshlrev_b32_e32 v72, 16, v63
	v_and_b32_e32 v73, 0xffff0000, v63
	v_mul_f32_e32 v37, v71, v71
	v_fmac_f32_e32 v37, v70, v70
	v_fmac_f32_e32 v37, v72, v72
	v_fmac_f32_e32 v37, v73, v73
	s_waitcnt vmcnt(6)
	v_lshlrev_b32_e32 v74, 16, v106
	v_and_b32_e32 v75, 0xffff0000, v106
	v_lshlrev_b32_e32 v76, 16, v107
	v_and_b32_e32 v77, 0xffff0000, v107
	v_mul_f32_e32 v43, v75, v75
	v_fmac_f32_e32 v43, v74, v74
	v_fmac_f32_e32 v43, v76, v76
	v_fmac_f32_e32 v43, v77, v77
	v_add_f32_e32 v37, v37, v43
	s_waitcnt vmcnt(5)
	v_lshlrev_b32_e32 v78, 16, v108
	v_and_b32_e32 v79, 0xffff0000, v108
	v_lshlrev_b32_e32 v80, 16, v109
	v_and_b32_e32 v81, 0xffff0000, v109
	v_mul_f32_e32 v43, v79, v79
	v_fmac_f32_e32 v43, v78, v78
	v_fmac_f32_e32 v43, v80, v80
	v_fmac_f32_e32 v43, v81, v81
	v_add_f32_e32 v37, v37, v43
	s_waitcnt vmcnt(0)
	v_lshlrev_b32_e32 v64, 16, v88
	v_and_b32_e32 v83, 0xffff0000, v110
	v_lshlrev_b32_e32 v82, 16, v110
	v_lshlrev_b32_e32 v84, 16, v111
	v_and_b32_e32 v85, 0xffff0000, v111
	v_mul_f32_e32 v43, v83, v83
	v_and_b32_e32 v63, 0xffff0000, v66
	v_and_b32_e32 v62, 0xffff0000, v88
	v_fmac_f32_e32 v43, v82, v82
	v_lshlrev_b32_e32 v65, 16, v66
	v_lshlrev_b32_e32 v68, 16, v89
	v_and_b32_e32 v66, 0xffff0000, v89
	v_pk_mul_f32 v[88:89], v[62:63], v[62:63]
	v_fmac_f32_e32 v43, v84, v84
	v_lshlrev_b32_e32 v69, 16, v67
	v_pk_fma_f32 v[88:89], v[64:65], v[64:65], v[88:89]
	v_fmac_f32_e32 v43, v85, v85
	v_and_b32_e32 v67, 0xffff0000, v67
	v_pk_fma_f32 v[88:89], v[68:69], v[68:69], v[88:89]
	v_add_f32_e32 v37, v37, v43
	v_pk_fma_f32 v[88:89], v[66:67], v[66:67], v[88:89]
	v_lshlrev_b32_e32 v87, 16, v92
	v_add_f32_e32 v37, v37, v88
	v_add_f32_e32 v37, v37, v89
	v_and_b32_e32 v89, 0xffff0000, v92
	v_and_b32_e32 v88, 0xffff0000, v102
	v_lshlrev_b32_e32 v86, 16, v102
	v_lshlrev_b32_e32 v90, 16, v103
	v_and_b32_e32 v92, 0xffff0000, v103
	v_pk_mul_f32 v[102:103], v[88:89], v[88:89]
	v_lshlrev_b32_e32 v91, 16, v93
	v_pk_fma_f32 v[102:103], v[86:87], v[86:87], v[102:103]
	v_and_b32_e32 v93, 0xffff0000, v93
	v_pk_fma_f32 v[102:103], v[90:91], v[90:91], v[102:103]
	s_nop 0
	v_pk_fma_f32 v[102:103], v[92:93], v[92:93], v[102:103]
	s_nop 0
	v_add_f32_e32 v37, v37, v102
	v_add_f32_e32 v37, v37, v103
	ds_bpermute_b32 v43, v96, v37
	ds_read_b128 v[102:105], v95
	s_waitcnt lgkmcnt(0)
	v_add_f32_e32 v37, v37, v43
	ds_bpermute_b32 v43, v97, v37
	s_waitcnt lgkmcnt(0)
; DI float wave_sum(float v) { v += __shfl_xor(v, 32); v += __shfl_xor(v, 16); v += __shfl_xor(v, 8); v += __shfl_xor(v, 4); v += __shfl_xor(v, 2); v += __shfl_xor(v, 1); return v; }
; DI void rownorm_phase(const Params& P, const float* xin, const bf16_t* yin, float* xout, bf16_t* hout, int lg, int gate_idx, const float* w_post,
;                       int lh, int scale_idx, int shift_idx, const float* w_pre, char* smem) {
;     ...
;       ss = wave_sum(ss); const float r = rsqrtf(ss * (1.f / 2048.f) + EPS);
; #pragma unroll
;       for (int j = 0; j < 8; ++j) { const f32x4 a = *(const f32x4*)(A1 + (j * 64 + lane) * 4); xv[j] += a * (yv[j] * r); }
;     }
;     if (yin || xout != xin) {
; #pragma unroll
;       for (int j = 0; j < 8; ++j) __builtin_nontemporal_store(xv[j], (f32x4*)(xout + (size_t)row * 2048 + (j * 64 + lane) * 4));
;     }
;     if (hout) {
;       float ss = 0.f;
; #pragma unroll
;       for (int j = 0; j < 8; ++j) ss += xv[j].x * xv[j].x + xv[j].y * xv[j].y + xv[j].z * xv[j].z + xv[j].w * xv[j].w;
;       ss = wave_sum(ss); const float r = rsqrtf(ss * (1.f / 2048.f) + EPS);
	v_add_f32_e32 v37, v37, v43
	ds_bpermute_b32 v43, v98, v37
	s_waitcnt lgkmcnt(0)
	v_add_f32_e32 v37, v37, v43
	ds_bpermute_b32 v43, v99, v37
	s_waitcnt lgkmcnt(0)
	v_add_f32_e32 v37, v37, v43
	ds_bpermute_b32 v43, v100, v37
	s_waitcnt lgkmcnt(0)
	v_add_f32_e32 v37, v37, v43
	ds_bpermute_b32 v43, v101, v37
	s_waitcnt lgkmcnt(0)
	v_add_f32_e32 v37, v37, v43
	v_fmamk_f32 v37, v37, 0x3a000000, v245
	v_cmp_gt_f32_e32 vcc, s84, v37
	v_mul_f32_e32 v43, 0x4b800000, v37
	s_nop 0
	v_cndmask_b32_e32 v37, v37, v43, vcc
	v_rsq_f32_e32 v37, v37
	s_nop 0
	v_mul_f32_e32 v43, 0x45800000, v37
	v_cndmask_b32_e32 v94, v37, v43, vcc
	v_pk_mul_f32 v[70:71], v[70:71], v[94:95] op_sel_hi:[1,0]
	v_pk_mul_f32 v[72:73], v[72:73], v[94:95] op_sel_hi:[1,0]
	v_pk_fma_f32 v[30:31], v[102:103], v[70:71], v[30:31]
	v_pk_fma_f32 v[32:33], v[104:105], v[72:73], v[32:33]
	ds_read_b128 v[70:73], v95 offset:1024
	v_pk_mul_f32 v[74:75], v[74:75], v[94:95] op_sel_hi:[1,0]
	v_pk_mul_f32 v[76:77], v[76:77], v[94:95] op_sel_hi:[1,0]
	v_mul_f32_e32 v37, v31, v31
	v_fmac_f32_e32 v37, v30, v30
	s_waitcnt lgkmcnt(0)
	v_pk_fma_f32 v[28:29], v[72:73], v[76:77], v[28:29]
	v_pk_fma_f32 v[26:27], v[70:71], v[74:75], v[26:27]
	ds_read_b128 v[70:73], v95 offset:2048
	v_pk_mul_f32 v[74:75], v[78:79], v[94:95] op_sel_hi:[1,0]
	v_pk_mul_f32 v[76:77], v[80:81], v[94:95] op_sel_hi:[1,0]
	v_mul_f32_e32 v43, v27, v27
	v_fmac_f32_e32 v43, v26, v26
	s_waitcnt lgkmcnt(0)
	v_pk_fma_f32 v[24:25], v[72:73], v[76:77], v[24:25]
	v_pk_fma_f32 v[22:23], v[70:71], v[74:75], v[22:23]
	ds_read_b128 v[70:73], v95 offset:3072
	v_pk_mul_f32 v[74:75], v[82:83], v[94:95] op_sel_hi:[1,0]
	v_pk_mul_f32 v[76:77], v[84:85], v[94:95] op_sel_hi:[1,0]
	v_fmac_f32_e32 v37, v32, v32
	v_fmac_f32_e32 v43, v28, v28
	s_waitcnt lgkmcnt(0)
	v_pk_fma_f32 v[20:21], v[72:73], v[76:77], v[20:21]
	v_pk_fma_f32 v[18:19], v[70:71], v[74:75], v[18:19]
	ds_read_b128 v[70:73], v95 offset:4096
	v_mov_b32_e32 v74, v64
	v_mov_b32_e32 v75, v62
	v_mov_b32_e32 v76, v68
	v_mov_b32_e32 v77, v66
	v_pk_mul_f32 v[74:75], v[74:75], v[94:95] op_sel_hi:[1,0]
	v_pk_mul_f32 v[76:77], v[76:77], v[94:95] op_sel_hi:[1,0]
	s_waitcnt lgkmcnt(0)
	v_pk_fma_f32 v[14:15], v[70:71], v[74:75], v[14:15]
	v_pk_fma_f32 v[16:17], v[72:73], v[76:77], v[16:17]
	ds_read_b128 v[70:73], v95 offset:5120
	v_mov_b32_e32 v62, v65
	v_mov_b32_e32 v66, v69
	v_pk_mul_f32 v[62:63], v[62:63], v[94:95] op_sel_hi:[1,0]
	v_pk_mul_f32 v[64:65], v[66:67], v[94:95] op_sel_hi:[1,0]
	s_waitcnt lgkmcnt(0)
	v_pk_fma_f32 v[10:11], v[70:71], v[62:63], v[10:11]
	v_pk_fma_f32 v[12:13], v[72:73], v[64:65], v[12:13]
	ds_read_b128 v[62:65], v95 offset:6144
	v_mov_b32_e32 v66, v86
	v_mov_b32_e32 v67, v88
	v_mov_b32_e32 v68, v90
	v_mov_b32_e32 v69, v92
	v_pk_mul_f32 v[66:67], v[66:67], v[94:95] op_sel_hi:[1,0]
	v_pk_mul_f32 v[68:69], v[68:69], v[94:95] op_sel_hi:[1,0]
	s_waitcnt lgkmcnt(0)
	v_pk_fma_f32 v[6:7], v[62:63], v[66:67], v[6:7]
	v_pk_fma_f32 v[8:9], v[64:65], v[68:69], v[8:9]
	ds_read_b128 v[62:65], v95 offset:7168
	v_fmac_f32_e32 v37, v33, v33
	v_fmac_f32_e32 v43, v29, v29
	v_add_f32_e32 v37, v37, v43
	v_mul_f32_e32 v43, v23, v23
	v_fmac_f32_e32 v43, v22, v22
	v_mov_b32_e32 v88, v87
	v_mov_b32_e32 v92, v91
	v_fmac_f32_e32 v43, v24, v24
	v_pk_mul_f32 v[66:67], v[88:89], v[94:95] op_sel_hi:[1,0]
	v_pk_mul_f32 v[68:69], v[92:93], v[94:95] op_sel_hi:[1,0]
	v_fmac_f32_e32 v43, v25, v25
	s_waitcnt lgkmcnt(0)
	v_pk_fma_f32 v[4:5], v[64:65], v[68:69], v[4:5]
	v_pk_fma_f32 v[2:3], v[62:63], v[66:67], v[2:3]
	global_store_dwordx4 v[52:53], v[30:33], off nt
	global_store_dwordx4 v[52:53], v[26:29], off offset:1024 nt
	global_store_dwordx4 v[52:53], v[22:25], off offset:2048 nt
	global_store_dwordx4 v[52:53], v[18:21], off offset:3072 nt
	global_store_dwordx4 v[54:55], v[14:17], off nt
	global_store_dwordx4 v[56:57], v[10:13], off nt
	global_store_dwordx4 v[58:59], v[6:9], off nt
	global_store_dwordx4 v[60:61], v[2:5], off nt
	v_add_f32_e32 v37, v43, v37
	v_mul_f32_e32 v43, v19, v19
	v_mov_b32_e32 v54, v11
	v_mov_b32_e32 v55, v15
	v_fmac_f32_e32 v43, v18, v18
	v_mov_b32_e32 v52, v10
	v_mov_b32_e32 v53, v14
	v_pk_mul_f32 v[54:55], v[54:55], v[54:55]
	v_fmac_f32_e32 v43, v20, v20
	v_pk_fma_f32 v[52:53], v[52:53], v[52:53], v[54:55]
	v_mov_b32_e32 v54, v12
	v_mov_b32_e32 v55, v16
	v_fmac_f32_e32 v43, v21, v21
	v_pk_fma_f32 v[52:53], v[54:55], v[54:55], v[52:53]
	v_mov_b32_e32 v54, v13
	v_mov_b32_e32 v55, v17
	v_add_f32_e32 v37, v43, v37
	v_pk_fma_f32 v[52:53], v[54:55], v[54:55], v[52:53]
	v_mov_b32_e32 v54, v3
	v_add_f32_e32 v37, v53, v37
	v_mov_b32_e32 v55, v7
	v_add_f32_e32 v37, v52, v37
	v_mov_b32_e32 v52, v2
	v_mov_b32_e32 v53, v6
	v_pk_mul_f32 v[54:55], v[54:55], v[54:55]
	s_nop 0
	v_pk_fma_f32 v[52:53], v[52:53], v[52:53], v[54:55]
	v_mov_b32_e32 v54, v4
	v_mov_b32_e32 v55, v8
	v_pk_fma_f32 v[52:53], v[54:55], v[54:55], v[52:53]
	v_mov_b32_e32 v54, v5
	v_mov_b32_e32 v55, v9
	v_pk_fma_f32 v[52:53], v[54:55], v[54:55], v[52:53]
	ds_read_b128 v[54:57], v95 offset:8192
	ds_read_b128 v[58:61], v95 offset:16384
	v_add_f32_e32 v37, v53, v37
	v_add_f32_e32 v37, v52, v37
	ds_bpermute_b32 v43, v96, v37
	s_waitcnt lgkmcnt(0)
; DI unsigned pack2(float lo, float hi) { f32x2 v = {lo, hi}; bf2_t b = __builtin_convertvector(v, bf2_t); return __builtin_bit_cast(unsigned, b); }
; DI float wave_sum(float v) { v += __shfl_xor(v, 32); v += __shfl_xor(v, 16); v += __shfl_xor(v, 8); v += __shfl_xor(v, 4); v += __shfl_xor(v, 2); v += __shfl_xor(v, 1); return v; }
; DI void rownorm_phase(const Params& P, const float* xin, const bf16_t* yin, float* xout, bf16_t* hout, int lg, int gate_idx, const float* w_post,
;                       int lh, int scale_idx, int shift_idx, const float* w_pre, char* smem) {
;     ...
;       ss = wave_sum(ss); const float r = rsqrtf(ss * (1.f / 2048.f) + EPS);
; #pragma unroll
;       for (int j = 0; j < 8; ++j) { const f32x4 a = *(const f32x4*)(A2 + (j * 64 + lane) * 4), b = *(const f32x4*)(B2 + (j * 64 + lane) * 4);
;         const f32x4 hv = xv[j] * r * a + b; u32x2 pk = {pack2(hv.x, hv.y), pack2(hv.z, hv.w)};
;         *(u32x2*)(hout + (size_t)row * 2048 + (j * 64 + lane) * 4) = pk; }
;     }
	v_add_f32_e32 v37, v37, v43
	ds_bpermute_b32 v43, v97, v37
	s_waitcnt lgkmcnt(0)
	v_add_f32_e32 v37, v37, v43
	ds_bpermute_b32 v43, v98, v37
	s_waitcnt lgkmcnt(0)
	v_add_f32_e32 v37, v37, v43
	ds_bpermute_b32 v43, v99, v37
	s_waitcnt lgkmcnt(0)
	v_add_f32_e32 v37, v37, v43
	ds_bpermute_b32 v43, v100, v37
	s_waitcnt lgkmcnt(0)
	v_add_f32_e32 v37, v37, v43
	ds_bpermute_b32 v43, v101, v37
	s_waitcnt lgkmcnt(0)
	v_add_f32_e32 v37, v37, v43
	v_fmamk_f32 v37, v37, 0x3a000000, v245
	v_cmp_gt_f32_e32 vcc, s84, v37
	v_mul_f32_e32 v43, 0x4b800000, v37
	s_nop 0
	v_cndmask_b32_e32 v37, v37, v43, vcc
	v_rsq_f32_e32 v37, v37
	s_nop 0
	v_mul_f32_e32 v43, 0x45800000, v37
	v_cndmask_b32_e32 v52, v37, v43, vcc
	v_pk_mul_f32 v[30:31], v[30:31], v[52:53] op_sel_hi:[1,0]
	v_pk_mul_f32 v[32:33], v[32:33], v[52:53] op_sel_hi:[1,0]
	v_pk_fma_f32 v[30:31], v[54:55], v[30:31], v[58:59]
	v_pk_fma_f32 v[32:33], v[56:57], v[32:33], v[60:61]
	v_cvt_pk_bf16_f32 v54, v30, v31
	v_cvt_pk_bf16_f32 v55, v32, v33
	v_lshl_add_u64 v[30:31], v[40:41], 0, v[50:51]
	global_store_dwordx2 v[30:31], v[54:55], off
	ds_read_b128 v[54:57], v95 offset:9216
	ds_read_b128 v[58:61], v95 offset:17408
	v_pk_mul_f32 v[26:27], v[26:27], v[52:53] op_sel_hi:[1,0]
	v_pk_mul_f32 v[28:29], v[28:29], v[52:53] op_sel_hi:[1,0]
	v_pk_mul_f32 v[22:23], v[22:23], v[52:53] op_sel_hi:[1,0]
	v_pk_mul_f32 v[24:25], v[24:25], v[52:53] op_sel_hi:[1,0]
	s_waitcnt lgkmcnt(0)
	v_pk_fma_f32 v[28:29], v[56:57], v[28:29], v[60:61]
	v_pk_fma_f32 v[26:27], v[54:55], v[26:27], v[58:59]
	v_pk_mul_f32 v[18:19], v[18:19], v[52:53] op_sel_hi:[1,0]
	v_cvt_pk_bf16_f32 v26, v26, v27
	v_cvt_pk_bf16_f32 v27, v28, v29
	global_store_dwordx2 v[30:31], v[26:27], off offset:512
	ds_read_b128 v[26:29], v95 offset:10240
	ds_read_b128 v[54:57], v95 offset:18432
	v_pk_mul_f32 v[20:21], v[20:21], v[52:53] op_sel_hi:[1,0]
	v_pk_mul_f32 v[14:15], v[14:15], v[52:53] op_sel_hi:[1,0]
	v_pk_mul_f32 v[16:17], v[16:17], v[52:53] op_sel_hi:[1,0]
	v_pk_mul_f32 v[10:11], v[10:11], v[52:53] op_sel_hi:[1,0]
	s_waitcnt lgkmcnt(0)
	v_pk_fma_f32 v[24:25], v[28:29], v[24:25], v[56:57]
	v_pk_fma_f32 v[22:23], v[26:27], v[22:23], v[54:55]
	v_pk_mul_f32 v[12:13], v[12:13], v[52:53] op_sel_hi:[1,0]
	v_cvt_pk_bf16_f32 v22, v22, v23
	v_cvt_pk_bf16_f32 v23, v24, v25
	global_store_dwordx2 v[30:31], v[22:23], off offset:1024
	ds_read_b128 v[22:25], v95 offset:11264
	ds_read_b128 v[26:29], v95 offset:19456
	v_pk_mul_f32 v[6:7], v[6:7], v[52:53] op_sel_hi:[1,0]
	v_pk_mul_f32 v[8:9], v[8:9], v[52:53] op_sel_hi:[1,0]
	v_pk_mul_f32 v[2:3], v[2:3], v[52:53] op_sel_hi:[1,0]
	v_pk_mul_f32 v[4:5], v[4:5], v[52:53] op_sel_hi:[1,0]
	s_waitcnt lgkmcnt(0)
	v_pk_fma_f32 v[20:21], v[24:25], v[20:21], v[28:29]
	v_pk_fma_f32 v[18:19], v[22:23], v[18:19], v[26:27]
	v_cmp_lt_i32_e32 vcc, s10, v36
	v_cvt_pk_bf16_f32 v18, v18, v19
	v_cvt_pk_bf16_f32 v19, v20, v21
	global_store_dwordx2 v[30:31], v[18:19], off offset:1536
	ds_read_b128 v[18:21], v95 offset:12288
	ds_read_b128 v[22:25], v95 offset:20480
	s_or_b64 s[8:9], vcc, s[8:9]
	s_waitcnt lgkmcnt(0)
	v_pk_fma_f32 v[16:17], v[20:21], v[16:17], v[24:25]
	v_pk_fma_f32 v[14:15], v[18:19], v[14:15], v[22:23]
	s_nop 0
	v_cvt_pk_bf16_f32 v14, v14, v15
	v_cvt_pk_bf16_f32 v15, v16, v17
	global_store_dwordx2 v[30:31], v[14:15], off offset:2048
	ds_read_b128 v[14:17], v95 offset:13312
	ds_read_b128 v[18:21], v95 offset:21504
	s_waitcnt lgkmcnt(0)
	v_pk_fma_f32 v[12:13], v[16:17], v[12:13], v[20:21]
	v_pk_fma_f32 v[10:11], v[14:15], v[10:11], v[18:19]
	s_nop 0
	v_cvt_pk_bf16_f32 v10, v10, v11
	v_cvt_pk_bf16_f32 v11, v12, v13
	global_store_dwordx2 v[30:31], v[10:11], off offset:2560
	ds_read_b128 v[10:13], v95 offset:14336
	ds_read_b128 v[14:17], v95 offset:22528
	s_waitcnt lgkmcnt(0)
	v_pk_fma_f32 v[8:9], v[12:13], v[8:9], v[16:17]
	v_pk_fma_f32 v[6:7], v[10:11], v[6:7], v[14:15]
	s_nop 0
	v_cvt_pk_bf16_f32 v6, v6, v7
	v_cvt_pk_bf16_f32 v7, v8, v9
	global_store_dwordx2 v[30:31], v[6:7], off offset:3072
	ds_read_b128 v[6:9], v95 offset:15360
	ds_read_b128 v[10:13], v95 offset:23552
	s_waitcnt lgkmcnt(0)
	v_pk_fma_f32 v[4:5], v[8:9], v[4:5], v[12:13]
	v_pk_fma_f32 v[2:3], v[6:7], v[2:3], v[10:11]
	s_nop 0
	v_cvt_pk_bf16_f32 v2, v2, v3
	v_cvt_pk_bf16_f32 v3, v4, v5
	global_store_dwordx2 v[30:31], v[2:3], off offset:3584
	s_andn2_b64 exec, exec, s[8:9]
	s_cbranch_execnz .LBB0_889

; DI float bflo(unsigned u) { return __uint_as_float(u << 16); }
; DI float bfhi(unsigned u) { return __uint_as_float(u & 0xffff0000u); }
; DI float wave_sum(float v) { v += __shfl_xor(v, 32); v += __shfl_xor(v, 16); v += __shfl_xor(v, 8); v += __shfl_xor(v, 4); v += __shfl_xor(v, 2); v += __shfl_xor(v, 1); return v; }
; DI void rownorm_phase(const Params& P, const float* xin, const bf16_t* yin, float* xout, bf16_t* hout, int lg, int gate_idx, const float* w_post,
;                       int lh, int scale_idx, int shift_idx, const float* w_pre, char* smem) {
;     ...
;   for (int row = blockIdx.x * 8 + w; row < S_; row += gridDim.x * 8) {
;     f32x4 xv[8];
; #pragma unroll
;     for (int j = 0; j < 8; ++j) xv[j] = __builtin_nontemporal_load((const f32x4*)(xin + (size_t)row * 2048 + (j * 64 + lane) * 4));
;     if (yin) {
;       f32x4 yv[8]; float ss = 0.f;
; #pragma unroll
;       for (int j = 0; j < 8; ++j) { const u32x2 yb = __builtin_nontemporal_load((const u32x2*)(yin + (size_t)row * 2048 + (j * 64 + lane) * 4)); yv[j] = (f32x4){bflo(yb.x), bfhi(yb.x), bflo(yb.y), bfhi(yb.y)};
;         ss += yv[j].x * yv[j].x + yv[j].y * yv[j].y + yv[j].z * yv[j].z + yv[j].w * yv[j].w; }
;       ss = wave_sum(ss); const float r = rsqrtf(ss * (1.f / 2048.f) + EPS);
.LBB0_1157:
	v_ashrrev_i32_e32 v37, 31, v36
	v_lshlrev_b64 v[2:3], 13, v[36:37]
	v_lshl_add_u64 v[2:3], v[34:35], 0, v[2:3]
	v_lshlrev_b64 v[58:59], 12, v[36:37]
	v_lshl_add_u64 v[54:55], v[2:3], 0, v[0:1]
	v_lshl_add_u64 v[82:83], v[38:39], 0, v[58:59]
	global_load_dwordx4 v[30:33], v[54:55], off nt
	global_load_dwordx4 v[26:29], v[54:55], off offset:1024 nt
	global_load_dwordx4 v[22:25], v[54:55], off offset:2048 nt
	global_load_dwordx4 v[18:21], v[54:55], off offset:3072 nt
	global_load_dwordx2 v[58:59], v[82:83], off nt
	v_mov_b32_e32 v41, v1
	v_mov_b32_e32 v43, v1
	v_mov_b32_e32 v45, v1
	v_mov_b32_e32 v47, v1
	v_lshl_add_u64 v[56:57], v[2:3], 0, v[40:41]
	v_lshl_add_u64 v[50:51], v[2:3], 0, v[42:43]
	v_lshl_add_u64 v[48:49], v[2:3], 0, v[44:45]
	v_lshl_add_u64 v[52:53], v[2:3], 0, v[46:47]
	global_load_dwordx4 v[14:17], v[56:57], off nt
	global_load_dwordx4 v[2:5], v[52:53], off nt
	global_load_dwordx4 v[10:13], v[50:51], off nt
	global_load_dwordx4 v[6:9], v[48:49], off nt
	v_add_u32_e32 v36, s79, v36
	global_load_dwordx2 v[106:107], v[82:83], off offset:512 nt
	global_load_dwordx2 v[108:109], v[82:83], off offset:1024 nt
	global_load_dwordx2 v[110:111], v[82:83], off offset:1536 nt
	global_load_dwordx2 v[84:85], v[82:83], off offset:2048 nt
	global_load_dwordx2 v[62:63], v[82:83], off offset:2560 nt
	global_load_dwordx2 v[98:99], v[82:83], off offset:3072 nt
	global_load_dwordx2 v[88:89], v[82:83], off offset:3584 nt
	s_waitcnt vmcnt(11)
	v_lshlrev_b32_e32 v66, 16, v58
	v_and_b32_e32 v67, 0xffff0000, v58
	v_lshlrev_b32_e32 v68, 16, v59
	v_and_b32_e32 v69, 0xffff0000, v59
	v_mul_f32_e32 v37, v67, v67
	v_fmac_f32_e32 v37, v66, v66
	v_fmac_f32_e32 v37, v68, v68
	v_fmac_f32_e32 v37, v69, v69
	s_waitcnt vmcnt(6)
	v_lshlrev_b32_e32 v70, 16, v106
	v_and_b32_e32 v71, 0xffff0000, v106
	v_lshlrev_b32_e32 v72, 16, v107
	v_and_b32_e32 v73, 0xffff0000, v107
	v_mul_f32_e32 v41, v71, v71
	v_fmac_f32_e32 v41, v70, v70
	v_fmac_f32_e32 v41, v72, v72
	v_fmac_f32_e32 v41, v73, v73
	v_add_f32_e32 v37, v37, v41
	s_waitcnt vmcnt(5)
	v_lshlrev_b32_e32 v74, 16, v108
	v_and_b32_e32 v75, 0xffff0000, v108
	v_lshlrev_b32_e32 v76, 16, v109
	v_and_b32_e32 v77, 0xffff0000, v109
	v_mul_f32_e32 v41, v75, v75
	v_fmac_f32_e32 v41, v74, v74
	v_fmac_f32_e32 v41, v76, v76
	v_fmac_f32_e32 v41, v77, v77
	v_add_f32_e32 v37, v37, v41
	s_waitcnt vmcnt(0)
	v_lshlrev_b32_e32 v60, 16, v84
	v_and_b32_e32 v79, 0xffff0000, v110
	v_lshlrev_b32_e32 v78, 16, v110
	v_lshlrev_b32_e32 v80, 16, v111
	v_and_b32_e32 v81, 0xffff0000, v111
	v_mul_f32_e32 v41, v79, v79
	v_and_b32_e32 v59, 0xffff0000, v62
	v_and_b32_e32 v58, 0xffff0000, v84
	v_fmac_f32_e32 v41, v78, v78
	v_lshlrev_b32_e32 v61, 16, v62
	v_lshlrev_b32_e32 v64, 16, v85
	v_and_b32_e32 v62, 0xffff0000, v85
	v_pk_mul_f32 v[84:85], v[58:59], v[58:59]
	v_fmac_f32_e32 v41, v80, v80
	v_lshlrev_b32_e32 v65, 16, v63
	v_pk_fma_f32 v[84:85], v[60:61], v[60:61], v[84:85]
	v_fmac_f32_e32 v41, v81, v81
	v_and_b32_e32 v63, 0xffff0000, v63
	v_pk_fma_f32 v[84:85], v[64:65], v[64:65], v[84:85]
	v_add_f32_e32 v37, v37, v41
	v_pk_fma_f32 v[84:85], v[62:63], v[62:63], v[84:85]
	v_lshlrev_b32_e32 v83, 16, v88
	v_add_f32_e32 v37, v37, v84
	v_add_f32_e32 v37, v37, v85
	v_and_b32_e32 v85, 0xffff0000, v88
	v_and_b32_e32 v84, 0xffff0000, v98
	v_lshlrev_b32_e32 v82, 16, v98
	v_lshlrev_b32_e32 v86, 16, v99
	v_and_b32_e32 v88, 0xffff0000, v99
	v_pk_mul_f32 v[98:99], v[84:85], v[84:85]
	v_lshlrev_b32_e32 v87, 16, v89
	v_pk_fma_f32 v[98:99], v[82:83], v[82:83], v[98:99]
	v_and_b32_e32 v89, 0xffff0000, v89
	v_pk_fma_f32 v[98:99], v[86:87], v[86:87], v[98:99]
	s_nop 0
	v_pk_fma_f32 v[98:99], v[88:89], v[88:89], v[98:99]
	s_nop 0
	v_add_f32_e32 v37, v37, v98
	v_add_f32_e32 v37, v37, v99
	ds_bpermute_b32 v41, v92, v37
	ds_read_b128 v[98:101], v91
	s_waitcnt lgkmcnt(0)
; DI float wave_sum(float v) { v += __shfl_xor(v, 32); v += __shfl_xor(v, 16); v += __shfl_xor(v, 8); v += __shfl_xor(v, 4); v += __shfl_xor(v, 2); v += __shfl_xor(v, 1); return v; }
; DI void rownorm_phase(const Params& P, const float* xin, const bf16_t* yin, float* xout, bf16_t* hout, int lg, int gate_idx, const float* w_post,
;                       int lh, int scale_idx, int shift_idx, const float* w_pre, char* smem) {
;     ...
;       ss = wave_sum(ss); const float r = rsqrtf(ss * (1.f / 2048.f) + EPS);
; #pragma unroll
;       for (int j = 0; j < 8; ++j) { const f32x4 a = *(const f32x4*)(A1 + (j * 64 + lane) * 4); xv[j] += a * (yv[j] * r); }
;     }
;     if (yin || xout != xin) {
; #pragma unroll
;       for (int j = 0; j < 8; ++j) __builtin_nontemporal_store(xv[j], (f32x4*)(xout + (size_t)row * 2048 + (j * 64 + lane) * 4));
;     }
	v_add_f32_e32 v37, v37, v41
	ds_bpermute_b32 v41, v93, v37
	s_waitcnt lgkmcnt(0)
	v_add_f32_e32 v37, v37, v41
	ds_bpermute_b32 v41, v94, v37
	s_waitcnt lgkmcnt(0)
	v_add_f32_e32 v37, v37, v41
	ds_bpermute_b32 v41, v95, v37
	s_waitcnt lgkmcnt(0)
	v_add_f32_e32 v37, v37, v41
	ds_bpermute_b32 v41, v96, v37
	s_waitcnt lgkmcnt(0)
	v_add_f32_e32 v37, v37, v41
	ds_bpermute_b32 v41, v97, v37
	s_waitcnt lgkmcnt(0)
	v_add_f32_e32 v37, v37, v41
	v_fmamk_f32 v37, v37, 0x3a000000, v245
	v_cmp_gt_f32_e32 vcc, s84, v37
	v_mul_f32_e32 v41, 0x4b800000, v37
	s_nop 0
	v_cndmask_b32_e32 v37, v37, v41, vcc
	v_rsq_f32_e32 v37, v37
	s_nop 0
	v_mul_f32_e32 v41, 0x45800000, v37
	v_cndmask_b32_e32 v90, v37, v41, vcc
	v_pk_mul_f32 v[66:67], v[66:67], v[90:91] op_sel_hi:[1,0]
	v_pk_mul_f32 v[68:69], v[68:69], v[90:91] op_sel_hi:[1,0]
	v_pk_fma_f32 v[30:31], v[98:99], v[66:67], v[30:31]
	v_pk_fma_f32 v[32:33], v[100:101], v[68:69], v[32:33]
	ds_read_b128 v[66:69], v91 offset:1024
	v_pk_mul_f32 v[70:71], v[70:71], v[90:91] op_sel_hi:[1,0]
	v_pk_mul_f32 v[72:73], v[72:73], v[90:91] op_sel_hi:[1,0]
	v_cmp_lt_i32_e32 vcc, s4, v36
	s_or_b64 s[2:3], vcc, s[2:3]
	s_waitcnt lgkmcnt(0)
	v_pk_fma_f32 v[28:29], v[68:69], v[72:73], v[28:29]
	v_pk_fma_f32 v[26:27], v[66:67], v[70:71], v[26:27]
	ds_read_b128 v[66:69], v91 offset:2048
	v_pk_mul_f32 v[70:71], v[74:75], v[90:91] op_sel_hi:[1,0]
	v_pk_mul_f32 v[72:73], v[76:77], v[90:91] op_sel_hi:[1,0]
	s_waitcnt lgkmcnt(0)
	v_pk_fma_f32 v[22:23], v[66:67], v[70:71], v[22:23]
	v_pk_fma_f32 v[24:25], v[68:69], v[72:73], v[24:25]
	ds_read_b128 v[66:69], v91 offset:3072
	v_pk_mul_f32 v[70:71], v[78:79], v[90:91] op_sel_hi:[1,0]
	v_pk_mul_f32 v[72:73], v[80:81], v[90:91] op_sel_hi:[1,0]
	s_waitcnt lgkmcnt(0)
	v_pk_fma_f32 v[18:19], v[66:67], v[70:71], v[18:19]
	v_pk_fma_f32 v[20:21], v[68:69], v[72:73], v[20:21]
	ds_read_b128 v[66:69], v91 offset:4096
	v_mov_b32_e32 v70, v60
	v_mov_b32_e32 v71, v58
	v_mov_b32_e32 v72, v64
	v_mov_b32_e32 v73, v62
	v_pk_mul_f32 v[70:71], v[70:71], v[90:91] op_sel_hi:[1,0]
	v_pk_mul_f32 v[72:73], v[72:73], v[90:91] op_sel_hi:[1,0]
	s_waitcnt lgkmcnt(0)
	v_pk_fma_f32 v[14:15], v[66:67], v[70:71], v[14:15]
	v_pk_fma_f32 v[16:17], v[68:69], v[72:73], v[16:17]
	ds_read_b128 v[66:69], v91 offset:5120
	v_mov_b32_e32 v58, v61
	v_mov_b32_e32 v62, v65
	v_pk_mul_f32 v[58:59], v[58:59], v[90:91] op_sel_hi:[1,0]
	v_pk_mul_f32 v[60:61], v[62:63], v[90:91] op_sel_hi:[1,0]
	s_waitcnt lgkmcnt(0)
	v_pk_fma_f32 v[10:11], v[66:67], v[58:59], v[10:11]
	v_pk_fma_f32 v[12:13], v[68:69], v[60:61], v[12:13]
	ds_read_b128 v[58:61], v91 offset:6144
	v_mov_b32_e32 v62, v82
	v_mov_b32_e32 v63, v84
	v_mov_b32_e32 v64, v86
	v_mov_b32_e32 v65, v88
	v_pk_mul_f32 v[62:63], v[62:63], v[90:91] op_sel_hi:[1,0]
	v_pk_mul_f32 v[64:65], v[64:65], v[90:91] op_sel_hi:[1,0]
	s_waitcnt lgkmcnt(0)
	v_pk_fma_f32 v[6:7], v[58:59], v[62:63], v[6:7]
	v_pk_fma_f32 v[8:9], v[60:61], v[64:65], v[8:9]
	ds_read_b128 v[58:61], v91 offset:7168
	v_mov_b32_e32 v84, v83
	v_mov_b32_e32 v88, v87
	v_pk_mul_f32 v[62:63], v[84:85], v[90:91] op_sel_hi:[1,0]
	v_pk_mul_f32 v[64:65], v[88:89], v[90:91] op_sel_hi:[1,0]
	s_waitcnt lgkmcnt(0)
	v_pk_fma_f32 v[2:3], v[58:59], v[62:63], v[2:3]
	v_pk_fma_f32 v[4:5], v[60:61], v[64:65], v[4:5]
	global_store_dwordx4 v[54:55], v[30:33], off nt
	global_store_dwordx4 v[54:55], v[26:29], off offset:1024 nt
	global_store_dwordx4 v[54:55], v[22:25], off offset:2048 nt
	global_store_dwordx4 v[54:55], v[18:21], off offset:3072 nt
	global_store_dwordx4 v[56:57], v[14:17], off nt
	global_store_dwordx4 v[50:51], v[10:13], off nt
	global_store_dwordx4 v[48:49], v[6:9], off nt
	global_store_dwordx4 v[52:53], v[2:5], off nt
	s_andn2_b64 exec, exec, s[2:3]
	s_cbranch_execnz .LBB0_1157

; DI float bflo(unsigned u) { return __uint_as_float(u << 16); }
; DI float bfhi(unsigned u) { return __uint_as_float(u & 0xffff0000u); }
; DI float wave_sum(float v) { v += __shfl_xor(v, 32); v += __shfl_xor(v, 16); v += __shfl_xor(v, 8); v += __shfl_xor(v, 4); v += __shfl_xor(v, 2); v += __shfl_xor(v, 1); return v; }
; DI void rownorm_phase(const Params& P, const float* xin, const bf16_t* yin, float* xout, bf16_t* hout, int lg, int gate_idx, const float* w_post,
;                       int lh, int scale_idx, int shift_idx, const float* w_pre, char* smem) {
;     ...
;   for (int row = blockIdx.x * 8 + w; row < S_; row += gridDim.x * 8) {
;     f32x4 xv[8];
; #pragma unroll
;     for (int j = 0; j < 8; ++j) xv[j] = __builtin_nontemporal_load((const f32x4*)(xin + (size_t)row * 2048 + (j * 64 + lane) * 4));
;     if (yin) {
;       f32x4 yv[8]; float ss = 0.f;
; #pragma unroll
;       for (int j = 0; j < 8; ++j) { const u32x2 yb = __builtin_nontemporal_load((const u32x2*)(yin + (size_t)row * 2048 + (j * 64 + lane) * 4)); yv[j] = (f32x4){bflo(yb.x), bfhi(yb.x), bflo(yb.y), bfhi(yb.y)};
;         ss += yv[j].x * yv[j].x + yv[j].y * yv[j].y + yv[j].z * yv[j].z + yv[j].w * yv[j].w; }
;       ss = wave_sum(ss); const float r = rsqrtf(ss * (1.f / 2048.f) + EPS);
; #pragma unroll
;       for (int j = 0; j < 8; ++j) { const f32x4 a = *(const f32x4*)(A1 + (j * 64 + lane) * 4); xv[j] += a * (yv[j] * r); }
.LBB0_1236:
	v_ashrrev_i32_e32 v37, 31, v36
	v_lshlrev_b64 v[2:3], 13, v[36:37]
	v_lshl_add_u64 v[2:3], v[34:35], 0, v[2:3]
	v_lshlrev_b64 v[50:51], 12, v[36:37]
	v_lshl_add_u64 v[52:53], v[2:3], 0, v[0:1]
	v_lshl_add_u64 v[86:87], v[38:39], 0, v[50:51]
	global_load_dwordx4 v[30:33], v[52:53], off nt
	global_load_dwordx4 v[26:29], v[52:53], off offset:1024 nt
	global_load_dwordx4 v[22:25], v[52:53], off offset:2048 nt
	global_load_dwordx4 v[18:21], v[52:53], off offset:3072 nt
	global_load_dwordx2 v[62:63], v[86:87], off nt
	v_mov_b32_e32 v43, v1
	v_mov_b32_e32 v45, v1
	v_mov_b32_e32 v47, v1
	v_mov_b32_e32 v49, v1
	v_lshl_add_u64 v[54:55], v[2:3], 0, v[42:43]
	v_lshl_add_u64 v[56:57], v[2:3], 0, v[44:45]
	v_lshl_add_u64 v[58:59], v[2:3], 0, v[46:47]
	v_lshl_add_u64 v[60:61], v[2:3], 0, v[48:49]
	global_load_dwordx4 v[14:17], v[54:55], off nt
	global_load_dwordx4 v[10:13], v[56:57], off nt
	global_load_dwordx4 v[6:9], v[58:59], off nt
	global_load_dwordx4 v[2:5], v[60:61], off nt
	v_add_u32_e32 v36, s79, v36
	global_load_dwordx2 v[106:107], v[86:87], off offset:512 nt
	global_load_dwordx2 v[108:109], v[86:87], off offset:1024 nt
	global_load_dwordx2 v[110:111], v[86:87], off offset:1536 nt
	global_load_dwordx2 v[88:89], v[86:87], off offset:2048 nt
	global_load_dwordx2 v[66:67], v[86:87], off offset:2560 nt
	global_load_dwordx2 v[102:103], v[86:87], off offset:3072 nt
	global_load_dwordx2 v[92:93], v[86:87], off offset:3584 nt
	s_waitcnt vmcnt(11)
	v_lshlrev_b32_e32 v70, 16, v62
	v_and_b32_e32 v71, 0xffff0000, v62
	v_lshlrev_b32_e32 v72, 16, v63
	v_and_b32_e32 v73, 0xffff0000, v63
	v_mul_f32_e32 v37, v71, v71
	v_fmac_f32_e32 v37, v70, v70
	v_fmac_f32_e32 v37, v72, v72
	v_fmac_f32_e32 v37, v73, v73
	s_waitcnt vmcnt(6)
	v_lshlrev_b32_e32 v74, 16, v106
	v_and_b32_e32 v75, 0xffff0000, v106
	v_lshlrev_b32_e32 v76, 16, v107
	v_and_b32_e32 v77, 0xffff0000, v107
	v_mul_f32_e32 v43, v75, v75
	v_fmac_f32_e32 v43, v74, v74
	v_fmac_f32_e32 v43, v76, v76
	v_fmac_f32_e32 v43, v77, v77
	v_add_f32_e32 v37, v37, v43
	s_waitcnt vmcnt(5)
	v_lshlrev_b32_e32 v78, 16, v108
	v_and_b32_e32 v79, 0xffff0000, v108
	v_lshlrev_b32_e32 v80, 16, v109
	v_and_b32_e32 v81, 0xffff0000, v109
	v_mul_f32_e32 v43, v79, v79
	v_fmac_f32_e32 v43, v78, v78
	v_fmac_f32_e32 v43, v80, v80
	v_fmac_f32_e32 v43, v81, v81
	v_add_f32_e32 v37, v37, v43
	s_waitcnt vmcnt(0)
	v_lshlrev_b32_e32 v64, 16, v88
	v_and_b32_e32 v83, 0xffff0000, v110
	v_lshlrev_b32_e32 v82, 16, v110
	v_lshlrev_b32_e32 v84, 16, v111
	v_and_b32_e32 v85, 0xffff0000, v111
	v_mul_f32_e32 v43, v83, v83
	v_and_b32_e32 v63, 0xffff0000, v66
	v_and_b32_e32 v62, 0xffff0000, v88
	v_fmac_f32_e32 v43, v82, v82
	v_lshlrev_b32_e32 v65, 16, v66
	v_lshlrev_b32_e32 v68, 16, v89
	v_and_b32_e32 v66, 0xffff0000, v89
	v_pk_mul_f32 v[88:89], v[62:63], v[62:63]
	v_fmac_f32_e32 v43, v84, v84
	v_lshlrev_b32_e32 v69, 16, v67
	v_pk_fma_f32 v[88:89], v[64:65], v[64:65], v[88:89]
	v_fmac_f32_e32 v43, v85, v85
	v_and_b32_e32 v67, 0xffff0000, v67
	v_pk_fma_f32 v[88:89], v[68:69], v[68:69], v[88:89]
	v_add_f32_e32 v37, v37, v43
	v_pk_fma_f32 v[88:89], v[66:67], v[66:67], v[88:89]
	v_lshlrev_b32_e32 v87, 16, v92
	v_add_f32_e32 v37, v37, v88
	v_add_f32_e32 v37, v37, v89
	v_and_b32_e32 v89, 0xffff0000, v92
	v_and_b32_e32 v88, 0xffff0000, v102
	v_lshlrev_b32_e32 v86, 16, v102
	v_lshlrev_b32_e32 v90, 16, v103
	v_and_b32_e32 v92, 0xffff0000, v103
	v_pk_mul_f32 v[102:103], v[88:89], v[88:89]
	v_lshlrev_b32_e32 v91, 16, v93
	v_pk_fma_f32 v[102:103], v[86:87], v[86:87], v[102:103]
	v_and_b32_e32 v93, 0xffff0000, v93
	v_pk_fma_f32 v[102:103], v[90:91], v[90:91], v[102:103]
	s_nop 0
	v_pk_fma_f32 v[102:103], v[92:93], v[92:93], v[102:103]
	s_nop 0
	v_add_f32_e32 v37, v37, v102
	v_add_f32_e32 v37, v37, v103
	ds_bpermute_b32 v43, v96, v37
	ds_read_b128 v[102:105], v95
	s_waitcnt lgkmcnt(0)
	v_add_f32_e32 v37, v37, v43
	ds_bpermute_b32 v43, v97, v37
	s_waitcnt lgkmcnt(0)
	v_add_f32_e32 v37, v37, v43
	ds_bpermute_b32 v43, v98, v37
	s_waitcnt lgkmcnt(0)
	v_add_f32_e32 v37, v37, v43
	ds_bpermute_b32 v43, v99, v37
	s_waitcnt lgkmcnt(0)
	v_add_f32_e32 v37, v37, v43
	ds_bpermute_b32 v43, v100, v37
	s_waitcnt lgkmcnt(0)
	v_add_f32_e32 v37, v37, v43
	ds_bpermute_b32 v43, v101, v37
	s_waitcnt lgkmcnt(0)
	v_add_f32_e32 v37, v37, v43
	v_fmamk_f32 v37, v37, 0x3a000000, v245
	v_cmp_gt_f32_e32 vcc, s84, v37
	v_mul_f32_e32 v43, 0x4b800000, v37
	s_nop 0
	v_cndmask_b32_e32 v37, v37, v43, vcc
	v_rsq_f32_e32 v37, v37
	s_nop 0
	v_mul_f32_e32 v43, 0x45800000, v37
	v_cndmask_b32_e32 v94, v37, v43, vcc
	v_pk_mul_f32 v[70:71], v[70:71], v[94:95] op_sel_hi:[1,0]
	v_pk_mul_f32 v[72:73], v[72:73], v[94:95] op_sel_hi:[1,0]
	v_pk_fma_f32 v[30:31], v[102:103], v[70:71], v[30:31]
	v_pk_fma_f32 v[32:33], v[104:105], v[72:73], v[32:33]
	ds_read_b128 v[70:73], v95 offset:1024
	v_pk_mul_f32 v[74:75], v[74:75], v[94:95] op_sel_hi:[1,0]
	v_pk_mul_f32 v[76:77], v[76:77], v[94:95] op_sel_hi:[1,0]
	v_mul_f32_e32 v37, v31, v31
	v_fmac_f32_e32 v37, v30, v30
	s_waitcnt lgkmcnt(0)
	v_pk_fma_f32 v[28:29], v[72:73], v[76:77], v[28:29]
	v_pk_fma_f32 v[26:27], v[70:71], v[74:75], v[26:27]
	ds_read_b128 v[70:73], v95 offset:2048
	v_pk_mul_f32 v[74:75], v[78:79], v[94:95] op_sel_hi:[1,0]
	v_pk_mul_f32 v[76:77], v[80:81], v[94:95] op_sel_hi:[1,0]
	v_mul_f32_e32 v43, v27, v27
	v_fmac_f32_e32 v43, v26, v26
	s_waitcnt lgkmcnt(0)
	v_pk_fma_f32 v[24:25], v[72:73], v[76:77], v[24:25]
	v_pk_fma_f32 v[22:23], v[70:71], v[74:75], v[22:23]
	ds_read_b128 v[70:73], v95 offset:3072
	v_pk_mul_f32 v[74:75], v[82:83], v[94:95] op_sel_hi:[1,0]
	v_pk_mul_f32 v[76:77], v[84:85], v[94:95] op_sel_hi:[1,0]
	v_fmac_f32_e32 v37, v32, v32
	v_fmac_f32_e32 v43, v28, v28
	s_waitcnt lgkmcnt(0)
; DI float wave_sum(float v) { v += __shfl_xor(v, 32); v += __shfl_xor(v, 16); v += __shfl_xor(v, 8); v += __shfl_xor(v, 4); v += __shfl_xor(v, 2); v += __shfl_xor(v, 1); return v; }
; DI void rownorm_phase(const Params& P, const float* xin, const bf16_t* yin, float* xout, bf16_t* hout, int lg, int gate_idx, const float* w_post,
;                       int lh, int scale_idx, int shift_idx, const float* w_pre, char* smem) {
;     ...
;       for (int j = 0; j < 8; ++j) { const f32x4 a = *(const f32x4*)(A1 + (j * 64 + lane) * 4); xv[j] += a * (yv[j] * r); }
;     }
;     if (yin || xout != xin) {
; #pragma unroll
;       for (int j = 0; j < 8; ++j) __builtin_nontemporal_store(xv[j], (f32x4*)(xout + (size_t)row * 2048 + (j * 64 + lane) * 4));
;     }
;     if (hout) {
;       float ss = 0.f;
; #pragma unroll
;       for (int j = 0; j < 8; ++j) ss += xv[j].x * xv[j].x + xv[j].y * xv[j].y + xv[j].z * xv[j].z + xv[j].w * xv[j].w;
;       ss = wave_sum(ss); const float r = rsqrtf(ss * (1.f / 2048.f) + EPS);
	v_pk_fma_f32 v[20:21], v[72:73], v[76:77], v[20:21]
	v_pk_fma_f32 v[18:19], v[70:71], v[74:75], v[18:19]
	ds_read_b128 v[70:73], v95 offset:4096
	v_mov_b32_e32 v74, v64
	v_mov_b32_e32 v75, v62
	v_mov_b32_e32 v76, v68
	v_mov_b32_e32 v77, v66
	v_pk_mul_f32 v[74:75], v[74:75], v[94:95] op_sel_hi:[1,0]
	v_pk_mul_f32 v[76:77], v[76:77], v[94:95] op_sel_hi:[1,0]
	s_waitcnt lgkmcnt(0)
	v_pk_fma_f32 v[14:15], v[70:71], v[74:75], v[14:15]
	v_pk_fma_f32 v[16:17], v[72:73], v[76:77], v[16:17]
	ds_read_b128 v[70:73], v95 offset:5120
	v_mov_b32_e32 v62, v65
	v_mov_b32_e32 v66, v69
	v_pk_mul_f32 v[62:63], v[62:63], v[94:95] op_sel_hi:[1,0]
	v_pk_mul_f32 v[64:65], v[66:67], v[94:95] op_sel_hi:[1,0]
	s_waitcnt lgkmcnt(0)
	v_pk_fma_f32 v[10:11], v[70:71], v[62:63], v[10:11]
	v_pk_fma_f32 v[12:13], v[72:73], v[64:65], v[12:13]
	ds_read_b128 v[62:65], v95 offset:6144
	v_mov_b32_e32 v66, v86
	v_mov_b32_e32 v67, v88
	v_mov_b32_e32 v68, v90
	v_mov_b32_e32 v69, v92
	v_pk_mul_f32 v[66:67], v[66:67], v[94:95] op_sel_hi:[1,0]
	v_pk_mul_f32 v[68:69], v[68:69], v[94:95] op_sel_hi:[1,0]
	s_waitcnt lgkmcnt(0)
	v_pk_fma_f32 v[6:7], v[62:63], v[66:67], v[6:7]
	v_pk_fma_f32 v[8:9], v[64:65], v[68:69], v[8:9]
	ds_read_b128 v[62:65], v95 offset:7168
	v_fmac_f32_e32 v37, v33, v33
	v_fmac_f32_e32 v43, v29, v29
	v_add_f32_e32 v37, v37, v43
	v_mul_f32_e32 v43, v23, v23
	v_fmac_f32_e32 v43, v22, v22
	v_mov_b32_e32 v88, v87
	v_mov_b32_e32 v92, v91
	v_fmac_f32_e32 v43, v24, v24
	v_pk_mul_f32 v[66:67], v[88:89], v[94:95] op_sel_hi:[1,0]
	v_pk_mul_f32 v[68:69], v[92:93], v[94:95] op_sel_hi:[1,0]
	v_fmac_f32_e32 v43, v25, v25
	s_waitcnt lgkmcnt(0)
	v_pk_fma_f32 v[4:5], v[64:65], v[68:69], v[4:5]
	v_pk_fma_f32 v[2:3], v[62:63], v[66:67], v[2:3]
	global_store_dwordx4 v[52:53], v[30:33], off nt
	global_store_dwordx4 v[52:53], v[26:29], off offset:1024 nt
	global_store_dwordx4 v[52:53], v[22:25], off offset:2048 nt
	global_store_dwordx4 v[52:53], v[18:21], off offset:3072 nt
	global_store_dwordx4 v[54:55], v[14:17], off nt
	global_store_dwordx4 v[56:57], v[10:13], off nt
	global_store_dwordx4 v[58:59], v[6:9], off nt
	global_store_dwordx4 v[60:61], v[2:5], off nt
	v_add_f32_e32 v37, v43, v37
	v_mul_f32_e32 v43, v19, v19
	v_mov_b32_e32 v54, v11
	v_mov_b32_e32 v55, v15
	v_fmac_f32_e32 v43, v18, v18
	v_mov_b32_e32 v52, v10
	v_mov_b32_e32 v53, v14
	v_pk_mul_f32 v[54:55], v[54:55], v[54:55]
	v_fmac_f32_e32 v43, v20, v20
	v_pk_fma_f32 v[52:53], v[52:53], v[52:53], v[54:55]
	v_mov_b32_e32 v54, v12
	v_mov_b32_e32 v55, v16
	v_fmac_f32_e32 v43, v21, v21
	v_pk_fma_f32 v[52:53], v[54:55], v[54:55], v[52:53]
	v_mov_b32_e32 v54, v13
	v_mov_b32_e32 v55, v17
	v_add_f32_e32 v37, v43, v37
	v_pk_fma_f32 v[52:53], v[54:55], v[54:55], v[52:53]
	v_mov_b32_e32 v54, v3
	v_add_f32_e32 v37, v53, v37
	v_mov_b32_e32 v55, v7
	v_add_f32_e32 v37, v52, v37
	v_mov_b32_e32 v52, v2
	v_mov_b32_e32 v53, v6
	v_pk_mul_f32 v[54:55], v[54:55], v[54:55]
	s_nop 0
	v_pk_fma_f32 v[52:53], v[52:53], v[52:53], v[54:55]
	v_mov_b32_e32 v54, v4
	v_mov_b32_e32 v55, v8
	v_pk_fma_f32 v[52:53], v[54:55], v[54:55], v[52:53]
	v_mov_b32_e32 v54, v5
	v_mov_b32_e32 v55, v9
	v_pk_fma_f32 v[52:53], v[54:55], v[54:55], v[52:53]
	ds_read_b128 v[54:57], v95 offset:8192
	ds_read_b128 v[58:61], v95 offset:16384
	v_add_f32_e32 v37, v53, v37
	v_add_f32_e32 v37, v52, v37
	ds_bpermute_b32 v43, v96, v37
	s_waitcnt lgkmcnt(0)
	v_add_f32_e32 v37, v37, v43
	ds_bpermute_b32 v43, v97, v37
	s_waitcnt lgkmcnt(0)
	v_add_f32_e32 v37, v37, v43
	ds_bpermute_b32 v43, v98, v37
	s_waitcnt lgkmcnt(0)
	v_add_f32_e32 v37, v37, v43
	ds_bpermute_b32 v43, v99, v37
	s_waitcnt lgkmcnt(0)
	v_add_f32_e32 v37, v37, v43
	ds_bpermute_b32 v43, v100, v37
	s_waitcnt lgkmcnt(0)
	v_add_f32_e32 v37, v37, v43
	ds_bpermute_b32 v43, v101, v37
	s_waitcnt lgkmcnt(0)
; DI unsigned pack2(float lo, float hi) { f32x2 v = {lo, hi}; bf2_t b = __builtin_convertvector(v, bf2_t); return __builtin_bit_cast(unsigned, b); }
; DI float wave_sum(float v) { v += __shfl_xor(v, 32); v += __shfl_xor(v, 16); v += __shfl_xor(v, 8); v += __shfl_xor(v, 4); v += __shfl_xor(v, 2); v += __shfl_xor(v, 1); return v; }
; DI void rownorm_phase(const Params& P, const float* xin, const bf16_t* yin, float* xout, bf16_t* hout, int lg, int gate_idx, const float* w_post,
;                       int lh, int scale_idx, int shift_idx, const float* w_pre, char* smem) {
;     ...
;       ss = wave_sum(ss); const float r = rsqrtf(ss * (1.f / 2048.f) + EPS);
; #pragma unroll
;       for (int j = 0; j < 8; ++j) { const f32x4 a = *(const f32x4*)(A2 + (j * 64 + lane) * 4), b = *(const f32x4*)(B2 + (j * 64 + lane) * 4);
;         const f32x4 hv = xv[j] * r * a + b; u32x2 pk = {pack2(hv.x, hv.y), pack2(hv.z, hv.w)};
;         *(u32x2*)(hout + (size_t)row * 2048 + (j * 64 + lane) * 4) = pk; }
;     }
	v_add_f32_e32 v37, v37, v43
	v_fmamk_f32 v37, v37, 0x3a000000, v245
	v_cmp_gt_f32_e32 vcc, s84, v37
	v_mul_f32_e32 v43, 0x4b800000, v37
	s_nop 0
	v_cndmask_b32_e32 v37, v37, v43, vcc
	v_rsq_f32_e32 v37, v37
	s_nop 0
	v_mul_f32_e32 v43, 0x45800000, v37
	v_cndmask_b32_e32 v52, v37, v43, vcc
	v_pk_mul_f32 v[30:31], v[30:31], v[52:53] op_sel_hi:[1,0]
	v_pk_mul_f32 v[32:33], v[32:33], v[52:53] op_sel_hi:[1,0]
	v_pk_fma_f32 v[30:31], v[54:55], v[30:31], v[58:59]
	v_pk_fma_f32 v[32:33], v[56:57], v[32:33], v[60:61]
	v_cvt_pk_bf16_f32 v54, v30, v31
	v_cvt_pk_bf16_f32 v55, v32, v33
	v_lshl_add_u64 v[30:31], v[40:41], 0, v[50:51]
	global_store_dwordx2 v[30:31], v[54:55], off
	ds_read_b128 v[54:57], v95 offset:9216
	ds_read_b128 v[58:61], v95 offset:17408
	v_pk_mul_f32 v[26:27], v[26:27], v[52:53] op_sel_hi:[1,0]
	v_pk_mul_f32 v[28:29], v[28:29], v[52:53] op_sel_hi:[1,0]
	v_pk_mul_f32 v[22:23], v[22:23], v[52:53] op_sel_hi:[1,0]
	v_pk_mul_f32 v[24:25], v[24:25], v[52:53] op_sel_hi:[1,0]
	s_waitcnt lgkmcnt(0)
	v_pk_fma_f32 v[28:29], v[56:57], v[28:29], v[60:61]
	v_pk_fma_f32 v[26:27], v[54:55], v[26:27], v[58:59]
	v_pk_mul_f32 v[18:19], v[18:19], v[52:53] op_sel_hi:[1,0]
	v_cvt_pk_bf16_f32 v26, v26, v27
	v_cvt_pk_bf16_f32 v27, v28, v29
	global_store_dwordx2 v[30:31], v[26:27], off offset:512
	ds_read_b128 v[26:29], v95 offset:10240
	ds_read_b128 v[54:57], v95 offset:18432
	v_pk_mul_f32 v[20:21], v[20:21], v[52:53] op_sel_hi:[1,0]
	v_pk_mul_f32 v[14:15], v[14:15], v[52:53] op_sel_hi:[1,0]
	v_pk_mul_f32 v[16:17], v[16:17], v[52:53] op_sel_hi:[1,0]
	v_pk_mul_f32 v[10:11], v[10:11], v[52:53] op_sel_hi:[1,0]
	s_waitcnt lgkmcnt(0)
	v_pk_fma_f32 v[24:25], v[28:29], v[24:25], v[56:57]
	v_pk_fma_f32 v[22:23], v[26:27], v[22:23], v[54:55]
	v_pk_mul_f32 v[12:13], v[12:13], v[52:53] op_sel_hi:[1,0]
	v_cvt_pk_bf16_f32 v22, v22, v23
	v_cvt_pk_bf16_f32 v23, v24, v25
	global_store_dwordx2 v[30:31], v[22:23], off offset:1024
	ds_read_b128 v[22:25], v95 offset:11264
	ds_read_b128 v[26:29], v95 offset:19456
	v_pk_mul_f32 v[6:7], v[6:7], v[52:53] op_sel_hi:[1,0]
	v_pk_mul_f32 v[8:9], v[8:9], v[52:53] op_sel_hi:[1,0]
	v_pk_mul_f32 v[2:3], v[2:3], v[52:53] op_sel_hi:[1,0]
	v_pk_mul_f32 v[4:5], v[4:5], v[52:53] op_sel_hi:[1,0]
	s_waitcnt lgkmcnt(0)
	v_pk_fma_f32 v[20:21], v[24:25], v[20:21], v[28:29]
	v_pk_fma_f32 v[18:19], v[22:23], v[18:19], v[26:27]
	v_cmp_lt_i32_e32 vcc, s4, v36
	v_cvt_pk_bf16_f32 v18, v18, v19
	v_cvt_pk_bf16_f32 v19, v20, v21
	global_store_dwordx2 v[30:31], v[18:19], off offset:1536
	ds_read_b128 v[18:21], v95 offset:12288
	ds_read_b128 v[22:25], v95 offset:20480
	s_or_b64 s[2:3], vcc, s[2:3]
	s_waitcnt lgkmcnt(0)
	v_pk_fma_f32 v[16:17], v[20:21], v[16:17], v[24:25]
	v_pk_fma_f32 v[14:15], v[18:19], v[14:15], v[22:23]
	s_nop 0
	v_cvt_pk_bf16_f32 v14, v14, v15
	v_cvt_pk_bf16_f32 v15, v16, v17
	global_store_dwordx2 v[30:31], v[14:15], off offset:2048
	ds_read_b128 v[14:17], v95 offset:13312
	ds_read_b128 v[18:21], v95 offset:21504
	s_waitcnt lgkmcnt(0)
	v_pk_fma_f32 v[12:13], v[16:17], v[12:13], v[20:21]
	v_pk_fma_f32 v[10:11], v[14:15], v[10:11], v[18:19]
	s_nop 0
	v_cvt_pk_bf16_f32 v10, v10, v11
	v_cvt_pk_bf16_f32 v11, v12, v13
	global_store_dwordx2 v[30:31], v[10:11], off offset:2560
	ds_read_b128 v[10:13], v95 offset:14336
	ds_read_b128 v[14:17], v95 offset:22528
	s_waitcnt lgkmcnt(0)
	v_pk_fma_f32 v[8:9], v[12:13], v[8:9], v[16:17]
	v_pk_fma_f32 v[6:7], v[10:11], v[6:7], v[14:15]
	s_nop 0
	v_cvt_pk_bf16_f32 v6, v6, v7
	v_cvt_pk_bf16_f32 v7, v8, v9
	global_store_dwordx2 v[30:31], v[6:7], off offset:3072
	ds_read_b128 v[6:9], v95 offset:15360
	ds_read_b128 v[10:13], v95 offset:23552
	s_waitcnt lgkmcnt(0)
	v_pk_fma_f32 v[4:5], v[8:9], v[4:5], v[12:13]
	v_pk_fma_f32 v[2:3], v[6:7], v[2:3], v[10:11]
	s_nop 0
	v_cvt_pk_bf16_f32 v2, v2, v3
	v_cvt_pk_bf16_f32 v3, v4, v5
	global_store_dwordx2 v[30:31], v[2:3], off offset:3584
	s_andn2_b64 exec, exec, s[2:3]
	s_cbranch_execnz .LBB0_1236
